# MoBA V^T workspace stored in MFMA-fragment order (REG1 epilogue stores and PV loads fully coalesced); P3 stage-4 gate loads hoisted; weights batched
# speedup vs baseline: 1.0768x; 1.0394x over previous
; DI u32x2 pk4(f32x4 v) { u32x2 r; r.x = pk2(v[0], v[1]); r.y = pk2(v[2], v[3]); return r; }
; template <int REG>
; DI void epi_inproj(const Params& p, f32x4 (&acc)[2][2][4][2], int pm, int pn, LAS unsigned char* shm) {
;     ...
;     const bool isr = pn < 8;
;     f32x4 rs4[2][2];
; #pragma unroll
;     for (int bj = 0; bj < 2; ++bj)
; #pragma unroll
;       for (int n = 0; n < 2; ++n) rs4[bj][n] = *(const f32x4*)(rstd1 + T0 + 128 * bj + 32 * wc + 8 * fq + 4 * n);
; #pragma unroll
;     for (int bj = 0; bj < 2; ++bj) {
;       const int cB = 128 * bj + 32 * wc + 8 * fq;
; #pragma unroll
;       for (int ai = 0; ai < 2; ++ai)
; #pragma unroll
;         for (int m = 0; m < 4; ++m) { asm volatile("" ::: "memory");
;           const int rA = 128 * ai + 64 * wr + 16 * m + fr;
;           bf16_t* dst;
;           if (isr) { const int tl = cB & 127;
;             dst = (bf16_t*)(ws + OFF_VRT) + ((long)((b * 4 + (pn - 4)) * 64 + 2 * blk + (cB >> 7))) * 32768 + (((rA >> 4) * 4 + (tl >> 5)) * 64 + ((tl >> 3) & 3) * 16 + (rA & 15)) * 8; }
;           else dst = (bf16_t*)(ws + OFF_MVT) + ((long)(((b * 8 + (pn - 16) * 4 + (rA >> 6)) * 32 + blk) * 64 + (rA & 63))) * 256 + cB;
;           const u32x2 h0 = pk4(acc[ai][bj][m][0] * rs4[bj][0]), h1 = pk4(acc[ai][bj][m][1] * rs4[bj][1]);
;           *(u32x4*)dst = (u32x4){h0.x, h0.y, h1.x, h1.y};
;         }
.LBB0_255:
	s_lshl_b32 s4, s54, 8
	s_ashr_i32 s5, s4, 31
	v_mov_b32_e32 v169, v194
	s_ashr_i32 s55, s54, 5
	s_lshl_b64 s[4:5], s[4:5], 2
	s_add_u32 s4, s31, s4
	v_bfe_u32 v170, v169, 6, 2
	v_lshrrev_b32_e32 v98, 1, v169
	s_addc_u32 s5, s67, s5
	v_lshlrev_b32_e32 v148, 7, v170
	v_and_b32_e32 v152, 24, v98
	v_lshl_add_u64 v[96:97], s[4:5], 0, v[148:149]
	v_lshlrev_b32_e32 v148, 2, v152
	v_lshl_add_u64 v[100:101], v[96:97], 0, v[148:149]
	global_load_dwordx4 v[136:139], v[100:101], off offset:16
	global_load_dwordx4 v[140:143], v[100:101], off
	global_load_dwordx4 v[96:99], v[100:101], off offset:528
	s_nop 0
	global_load_dwordx4 v[100:103], v[100:101], off offset:512
	s_and_b32 s4, s54, 31
	s_cmp_gt_i32 s56, 7
	s_cselect_b64 s[58:59], -1, 0
	s_lshl_b32 s5, s55, 3
	s_lshl_b32 s54, s56, 2
	s_add_i32 s60, s54, s5
	s_lshl_b32 s5, s55, 8
	s_lshl_b32 s54, s56, 6
	s_lshl_b32 s61, s4, 6
	s_add_i32 s54, s54, s5
	s_lshl_b32 s4, s4, 1
	s_or_b32 s4, s54, s4
	s_add_i32 s54, s4, 0xffffff00
	v_and_b32_e32 v148, 63, v169
	v_lshlrev_b32_e32 v148, 4, v148

; template <int REG>
; DI void epi_inproj(const Params& p, f32x4 (&acc)[2][2][4][2], int pm, int pn, LAS unsigned char* shm) {
;     ...
;             dst = (bf16_t*)(ws + OFF_VRT) + ((long)((b * 4 + (pn - 4)) * 64 + 2 * blk + (cB >> 7))) * 32768 + (((rA >> 4) * 4 + (tl >> 5)) * 64 + ((tl >> 3) & 3) * 16 + (rA & 15)) * 8; }
;           else dst = (bf16_t*)(ws + OFF_MVT) + ((long)(((b * 8 + (pn - 16) * 4 + (rA >> 6)) * 32 + blk) * 64 + (rA & 63))) * 256 + cB;
	v_ashrrev_i32_e32 v172, 2, v169
	v_lshl_or_b32 v148, v170, 10, v148
	s_mov_b32 s100, 0x1000
	s_mov_b32 s101, 0

; template <int REG>
; DI void epi_inproj(const Params& p, f32x4 (&acc)[2][2][4][2], int pm, int pn, LAS unsigned char* shm) {
;     ...
;           const int rA = 128 * ai + 64 * wr + 16 * m + fr;
;           bf16_t* dst;
;           if (isr) { const int tl = cB & 127;
;             dst = (bf16_t*)(ws + OFF_VRT) + ((long)((b * 4 + (pn - 4)) * 64 + 2 * blk + (cB >> 7))) * 32768 + (((rA >> 4) * 4 + (tl >> 5)) * 64 + ((tl >> 3) & 3) * 16 + (rA & 15)) * 8; }
;           else dst = (bf16_t*)(ws + OFF_MVT) + ((long)(((b * 8 + (pn - 16) * 4 + (rA >> 6)) * 32 + blk) * 64 + (rA & 63))) * 256 + cB;
	s_ashr_i32 s55, s54, 31
	s_add_i32 s60, s60, 0x1fffc0
	v_lshl_add_u64 v[152:153], s[14:15], 0, v[148:149]
	s_lshl_b64 s[4:5], s[54:55], 16
	v_lshrrev_b32_e32 v148, 6, v172
	s_add_u32 s56, s82, s4
	v_add_u32_e32 v148, s60, v148
	v_mov_b32_e32 v171, 0

; template <int REG>
; DI void epi_inproj(const Params& p, f32x4 (&acc)[2][2][4][2], int pm, int pn, LAS unsigned char* shm) {
;     ...
;           else dst = (bf16_t*)(ws + OFF_MVT) + ((long)(((b * 8 + (pn - 16) * 4 + (rA >> 6)) * 32 + blk) * 64 + (rA & 63))) * 256 + cB;
	s_addc_u32 s57, s83, s5
	v_lshl_or_b32 v148, v148, 11, s61
	s_mov_b64 s[4:5], -1
	s_and_b64 vcc, exec, s[58:59]
	s_cbranch_vccz .LBB0_257
	v_or_b32_e32 v154, v148, v171
	v_ashrrev_i32_e32 v155, 31, v154
	v_lshlrev_b64 v[154:155], 9, v[154:155]
	v_lshl_add_u64 v[154:155], v[152:153], 0, v[154:155]
	s_mov_b64 s[4:5], 0

; DI u32x2 pk4(f32x4 v) { u32x2 r; r.x = pk2(v[0], v[1]); r.y = pk2(v[2], v[3]); return r; }
; template <int REG>
; DI void epi_inproj(const Params& p, f32x4 (&acc)[2][2][4][2], int pm, int pn, LAS unsigned char* shm) {
;     ...
;           const u32x2 h0 = pk4(acc[ai][bj][m][0] * rs4[bj][0]), h1 = pk4(acc[ai][bj][m][1] * rs4[bj][1]);
;           *(u32x4*)dst = (u32x4){h0.x, h0.y, h1.x, h1.y};
.LBB0_287:
	v_pk_mul_f32 v[70:71], v[70:71], v[142:143]
	v_pk_mul_f32 v[68:69], v[68:69], v[140:141]
	v_pk_mul_f32 v[62:63], v[62:63], v[138:139]
	v_pk_mul_f32 v[60:61], v[60:61], v[136:137]
	v_cvt_pk_bf16_f32 v68, v68, v69
	v_cvt_pk_bf16_f32 v69, v70, v71
	v_cvt_pk_bf16_f32 v70, v60, v61
	v_cvt_pk_bf16_f32 v71, v62, v63
	s_or_b32 s54, s54, 1
	global_store_dwordx4 v[72:73], v[68:71], off
	s_ashr_i32 s55, s54, 31
	s_lshl_b64 s[54:55], s[54:55], 16
	s_add_u32 s54, s82, s54
	s_addc_u32 s55, s83, s55
	s_and_b64 vcc, exec, s[4:5]
	s_mov_b64 s[56:57], -1
	s_cbranch_vccnz .LBB0_289
	v_or_b32_e32 v60, v148, v171
	v_ashrrev_i32_e32 v61, 31, v60
	v_lshlrev_b64 v[60:61], 9, v[60:61]
	v_lshl_add_u64 v[60:61], v[152:153], 0, v[60:61]
	v_lshl_add_u64 v[60:61], v[60:61], 0, s[100:101]
	s_mov_b64 s[56:57], 0

; DI u32x2 pk4(f32x4 v) { u32x2 r; r.x = pk2(v[0], v[1]); r.y = pk2(v[2], v[3]); return r; }
; template <int REG>
; DI void epi_inproj(const Params& p, f32x4 (&acc)[2][2][4][2], int pm, int pn, LAS unsigned char* shm) {
;     ...
;           const u32x2 h0 = pk4(acc[ai][bj][m][0] * rs4[bj][0]), h1 = pk4(acc[ai][bj][m][1] * rs4[bj][1]);
;           *(u32x4*)dst = (u32x4){h0.x, h0.y, h1.x, h1.y};
.LBB0_291:
	v_pk_mul_f32 v[66:67], v[66:67], v[102:103]
	v_pk_mul_f32 v[62:63], v[64:65], v[100:101]
	v_pk_mul_f32 v[58:59], v[58:59], v[98:99]
	v_pk_mul_f32 v[56:57], v[56:57], v[96:97]
	v_cvt_pk_bf16_f32 v62, v62, v63
	v_cvt_pk_bf16_f32 v63, v66, v67
	v_cvt_pk_bf16_f32 v64, v56, v57
	v_cvt_pk_bf16_f32 v65, v58, v59
	global_store_dwordx4 v[60:61], v[62:65], off
	s_and_b64 vcc, exec, s[4:5]
	s_mov_b64 s[56:57], -1
	s_cbranch_vccnz .LBB0_293
	v_or3_b32 v56, v171, v148, 16
	v_ashrrev_i32_e32 v57, 31, v56
	v_lshlrev_b64 v[56:57], 9, v[56:57]
	v_lshl_add_u64 v[56:57], v[152:153], 0, v[56:57]
	v_lshl_add_u64 v[56:57], v[56:57], 0, s[100:101]
	s_mov_b64 s[56:57], 0

; DI u32x2 pk4(f32x4 v) { u32x2 r; r.x = pk2(v[0], v[1]); r.y = pk2(v[2], v[3]); return r; }
; template <int REG>
; DI void epi_inproj(const Params& p, f32x4 (&acc)[2][2][4][2], int pm, int pn, LAS unsigned char* shm) {
;     ...
;           const u32x2 h0 = pk4(acc[ai][bj][m][0] * rs4[bj][0]), h1 = pk4(acc[ai][bj][m][1] * rs4[bj][1]);
;           *(u32x4*)dst = (u32x4){h0.x, h0.y, h1.x, h1.y};
.LBB0_295:
	v_pk_mul_f32 v[54:55], v[54:55], v[102:103]
	v_pk_mul_f32 v[52:53], v[52:53], v[100:101]
	v_pk_mul_f32 v[50:51], v[50:51], v[98:99]
	v_pk_mul_f32 v[48:49], v[48:49], v[96:97]
	v_cvt_pk_bf16_f32 v52, v52, v53
	v_cvt_pk_bf16_f32 v53, v54, v55
	v_cvt_pk_bf16_f32 v54, v48, v49
	v_cvt_pk_bf16_f32 v55, v50, v51
	global_store_dwordx4 v[56:57], v[52:55], off
	s_and_b64 vcc, exec, s[4:5]
	s_mov_b64 s[56:57], -1
	s_cbranch_vccnz .LBB0_297
	v_or3_b32 v48, v171, v148, 32
	v_ashrrev_i32_e32 v49, 31, v48
	v_lshlrev_b64 v[48:49], 9, v[48:49]
	v_lshl_add_u64 v[48:49], v[152:153], 0, v[48:49]
	v_lshl_add_u64 v[48:49], v[48:49], 0, s[100:101]
	s_mov_b64 s[56:57], 0

; DI u32x2 pk4(f32x4 v) { u32x2 r; r.x = pk2(v[0], v[1]); r.y = pk2(v[2], v[3]); return r; }
; template <int REG>
; DI void epi_inproj(const Params& p, f32x4 (&acc)[2][2][4][2], int pm, int pn, LAS unsigned char* shm) {
;     ...
;           const u32x2 h0 = pk4(acc[ai][bj][m][0] * rs4[bj][0]), h1 = pk4(acc[ai][bj][m][1] * rs4[bj][1]);
;           *(u32x4*)dst = (u32x4){h0.x, h0.y, h1.x, h1.y};
.LBB0_299:
	v_pk_mul_f32 v[46:47], v[46:47], v[102:103]
	v_pk_mul_f32 v[44:45], v[44:45], v[100:101]
	v_pk_mul_f32 v[42:43], v[42:43], v[98:99]
	v_pk_mul_f32 v[40:41], v[40:41], v[96:97]
	v_cvt_pk_bf16_f32 v44, v44, v45
	v_cvt_pk_bf16_f32 v45, v46, v47
	v_cvt_pk_bf16_f32 v46, v40, v41
	v_cvt_pk_bf16_f32 v47, v42, v43
	global_store_dwordx4 v[48:49], v[44:47], off
	s_and_b64 vcc, exec, s[4:5]
	s_mov_b64 s[56:57], -1
	s_cbranch_vccnz .LBB0_301
	v_or3_b32 v40, v171, v148, 48
	v_ashrrev_i32_e32 v41, 31, v40
	v_lshlrev_b64 v[40:41], 9, v[40:41]
	v_lshl_add_u64 v[40:41], v[152:153], 0, v[40:41]
	v_lshl_add_u64 v[40:41], v[40:41], 0, s[100:101]
	s_mov_b64 s[56:57], 0

; DI u32x2 pk4(f32x4 v) { u32x2 r; r.x = pk2(v[0], v[1]); r.y = pk2(v[2], v[3]); return r; }
; template <int REG>
; DI void epi_inproj(const Params& p, f32x4 (&acc)[2][2][4][2], int pm, int pn, LAS unsigned char* shm) {
;     ...
;           const u32x2 h0 = pk4(acc[ai][bj][m][0] * rs4[bj][0]), h1 = pk4(acc[ai][bj][m][1] * rs4[bj][1]);
;           *(u32x4*)dst = (u32x4){h0.x, h0.y, h1.x, h1.y};
.LBB0_303:
	v_pk_mul_f32 v[38:39], v[38:39], v[102:103]
	v_pk_mul_f32 v[36:37], v[36:37], v[100:101]
	v_pk_mul_f32 v[34:35], v[34:35], v[98:99]
	v_pk_mul_f32 v[32:33], v[32:33], v[96:97]
	v_cvt_pk_bf16_f32 v36, v36, v37
	v_cvt_pk_bf16_f32 v37, v38, v39
	v_cvt_pk_bf16_f32 v38, v32, v33
	v_cvt_pk_bf16_f32 v39, v34, v35
	global_store_dwordx4 v[40:41], v[36:39], off
	s_and_b64 vcc, exec, s[4:5]
	s_mov_b64 s[56:57], -1
	s_cbranch_vccnz .LBB0_305
	v_or_b32_e32 v32, v107, v171
	v_ashrrev_i32_e32 v33, 31, v32
	v_lshlrev_b64 v[32:33], 9, v[32:33]
	v_lshl_add_u64 v[32:33], v[152:153], 0, v[32:33]
	v_lshl_add_u64 v[32:33], v[32:33], 0, s[100:101]
	s_mov_b64 s[56:57], 0

; DI u32x2 pk4(f32x4 v) { u32x2 r; r.x = pk2(v[0], v[1]); r.y = pk2(v[2], v[3]); return r; }
; template <int REG>
; DI void epi_inproj(const Params& p, f32x4 (&acc)[2][2][4][2], int pm, int pn, LAS unsigned char* shm) {
;     ...
;           const u32x2 h0 = pk4(acc[ai][bj][m][0] * rs4[bj][0]), h1 = pk4(acc[ai][bj][m][1] * rs4[bj][1]);
;           *(u32x4*)dst = (u32x4){h0.x, h0.y, h1.x, h1.y};
.LBB0_307:
	v_pk_mul_f32 v[30:31], v[30:31], v[102:103]
	v_pk_mul_f32 v[28:29], v[28:29], v[100:101]
	v_pk_mul_f32 v[26:27], v[26:27], v[98:99]
	v_pk_mul_f32 v[24:25], v[24:25], v[96:97]
	v_cvt_pk_bf16_f32 v28, v28, v29
	v_cvt_pk_bf16_f32 v29, v30, v31
	v_cvt_pk_bf16_f32 v30, v24, v25
	v_cvt_pk_bf16_f32 v31, v26, v27
	global_store_dwordx4 v[32:33], v[28:31], off
	s_and_b64 vcc, exec, s[4:5]
	s_mov_b64 s[56:57], -1
	s_cbranch_vccnz .LBB0_309
	v_or3_b32 v24, v171, v107, 16
	v_ashrrev_i32_e32 v25, 31, v24
	v_lshlrev_b64 v[24:25], 9, v[24:25]
	v_lshl_add_u64 v[24:25], v[152:153], 0, v[24:25]
	v_lshl_add_u64 v[24:25], v[24:25], 0, s[100:101]
	s_mov_b64 s[56:57], 0

; DI u32x2 pk4(f32x4 v) { u32x2 r; r.x = pk2(v[0], v[1]); r.y = pk2(v[2], v[3]); return r; }
; template <int REG>
; DI void epi_inproj(const Params& p, f32x4 (&acc)[2][2][4][2], int pm, int pn, LAS unsigned char* shm) {
;     ...
;           const u32x2 h0 = pk4(acc[ai][bj][m][0] * rs4[bj][0]), h1 = pk4(acc[ai][bj][m][1] * rs4[bj][1]);
;           *(u32x4*)dst = (u32x4){h0.x, h0.y, h1.x, h1.y};
.LBB0_311:
	v_pk_mul_f32 v[22:23], v[22:23], v[102:103]
	v_pk_mul_f32 v[20:21], v[20:21], v[100:101]
	v_pk_mul_f32 v[18:19], v[18:19], v[98:99]
	v_pk_mul_f32 v[16:17], v[16:17], v[96:97]
	v_cvt_pk_bf16_f32 v20, v20, v21
	v_cvt_pk_bf16_f32 v21, v22, v23
	v_cvt_pk_bf16_f32 v22, v16, v17
	v_cvt_pk_bf16_f32 v23, v18, v19
	global_store_dwordx4 v[24:25], v[20:23], off
	s_and_b64 vcc, exec, s[4:5]
	s_mov_b64 s[56:57], -1
	s_cbranch_vccnz .LBB0_313
	v_or3_b32 v16, v171, v107, 32
	v_ashrrev_i32_e32 v17, 31, v16
	v_lshlrev_b64 v[16:17], 9, v[16:17]
	v_lshl_add_u64 v[16:17], v[152:153], 0, v[16:17]
	v_lshl_add_u64 v[16:17], v[16:17], 0, s[100:101]
	s_mov_b64 s[56:57], 0

; DI u32x2 pk4(f32x4 v) { u32x2 r; r.x = pk2(v[0], v[1]); r.y = pk2(v[2], v[3]); return r; }
; template <int REG>
; DI void epi_inproj(const Params& p, f32x4 (&acc)[2][2][4][2], int pm, int pn, LAS unsigned char* shm) {
;     ...
;           const u32x2 h0 = pk4(acc[ai][bj][m][0] * rs4[bj][0]), h1 = pk4(acc[ai][bj][m][1] * rs4[bj][1]);
;           *(u32x4*)dst = (u32x4){h0.x, h0.y, h1.x, h1.y};
.LBB0_315:
	v_pk_mul_f32 v[14:15], v[14:15], v[102:103]
	v_pk_mul_f32 v[12:13], v[12:13], v[100:101]
	v_pk_mul_f32 v[10:11], v[10:11], v[98:99]
	v_pk_mul_f32 v[8:9], v[8:9], v[96:97]
	v_cvt_pk_bf16_f32 v12, v12, v13
	v_cvt_pk_bf16_f32 v13, v14, v15
	v_cvt_pk_bf16_f32 v14, v8, v9
	v_cvt_pk_bf16_f32 v15, v10, v11
	global_store_dwordx4 v[16:17], v[12:15], off
	s_and_b64 vcc, exec, s[4:5]
	s_mov_b64 s[4:5], -1
	s_cbranch_vccnz .LBB0_317
	v_or3_b32 v8, v171, v107, 48
	v_ashrrev_i32_e32 v9, 31, v8
	v_lshlrev_b64 v[8:9], 9, v[8:9]
	v_lshl_add_u64 v[8:9], v[152:153], 0, v[8:9]
	v_lshl_add_u64 v[8:9], v[8:9], 0, s[100:101]
	s_mov_b64 s[4:5], 0

; #define LAS __attribute__((address_space(3)))
;     ...
;   int tid_ = threadIdx.x; asm volatile("" : "+v"(tid_)); const int tid = tid_, wid = __builtin_amdgcn_readfirstlane(tid >> 6), lane = tid & 63, fr = lane & 15, fq = lane >> 4;
;   const bf16_t* Mk = (const bf16_t*)(ws + OFF_MK); const bf16_t* Mvt = (const bf16_t*)(ws + OFF_MVT);
;   bf16_t* Mq = (bf16_t*)(ws + OFF_MQ);
;   const float* kbarg = (const float*)(ws + OFF_KBAR);
;   const float mb = ((const float*)(ws + OFF_SC))[0];
;   const float c2 = mb * 1.4426950408889634f;
;   LAS float* oacc = (LAS float*)(shm + MO_OACC); LAS float* lsl = (LAS float*)(shm + MO_L); LAS float* kb = (LAS float*)(shm + MO_KBAR);
;   LAS int* cnt = (LAS int*)(shm + MO_CNT); LAS unsigned char* list = shm + MO_LIST; LAS unsigned char* Qs = shm + MO_Q; LAS unsigned char* Pb = shm + MO_P;
;   const int dtw = wid & 3, ttw = wid >> 2;
;   for (int u = blockIdx.x, it = 0; u < 1024; u += gridDim.x, ++it) {
;     int blk = 31 - (u >> 5), bh = u & 31;
;     if (gridDim.x == 256) {
;       const int x = blockIdx.x & 7, m = blockIdx.x >> 3, m2 = (m + 16) & 31;
;       bh = x + 8 * it; blk = it == 0 ? 31 - m : (it == 1 ? m : (it == 2 ? m2 : 31 - m2));
;     }
;     const long qbase = ((long)bh * SEQ + blk * 256) * 64;
;     for (int i = tid; i < 256 * 64; i += NTHREADS) oacc[i] = 0.f;
;     if (tid < 256) lsl[tid] = 0.f;
;     if (tid < 32) cnt[tid] = 0;
;     for (int i = tid; i < blk * 64; i += NTHREADS) kb[i] = kbarg[((long)bh * 32) * 64 + i];
;     const int qt = tid >> 1, qh = tid & 1;
;     ...
;             const bf16_t* vp = Mvt + vrow + ((long)(j + 1) * 64 + dh * 32 + fr) * 256 + fq * 8;
.LBB0_539:
	v_mov_b32_e32 v184, v194
	s_cmpk_lt_i32 s2, 0x400
	s_cselect_b64 s[0:1], -1, 0
	s_cmpk_gt_i32 s2, 0x3ff
	v_readfirstlane_b32 s14, v184
	s_cbranch_scc1 .Lscan_entry
	s_waitcnt vmcnt(27)
	v_mov_b32_e32 v0, 0x1e7e0000
	global_load_dword v8, v0, s[26:27]
	s_add_u32 s58, s26, 0x1e7a0000
	s_addc_u32 s60, s27, 0
	s_ashr_i32 s15, s14, 6
	v_ashrrev_i32_e32 v0, 1, v184
	s_cmpk_eq_i32 s28, 0x100
	v_and_b32_e32 v4, 63, v184
	v_lshlrev_b32_e32 v5, 1, v184
	v_ashrrev_i32_e32 v1, 31, v0
	s_cselect_b64 s[40:41], -1, 0
	s_lshr_b32 s62, s2, 3
	v_and_b32_e32 v10, 1, v184
	v_lshlrev_b32_e32 v202, 4, v4
	v_cmp_gt_u32_e32 vcc, 16, v4
	s_waitcnt vmcnt(26)
	v_and_b32_e32 v13, 24, v5
	v_lshlrev_b64 v[4:5], 7, v[0:1]
	s_and_b32 s61, s2, 7
	s_bfe_u32 s63, s2, 0x50003
	s_add_i32 s21, 0, 0x10000
	s_add_i32 s22, 0, 0x10400
	s_add_i32 s23, 0, 0x12480
	s_sub_i32 s64, 31, s62
	v_mov_b32_e32 v187, 0
	v_lshlrev_b32_e32 v186, 6, v10
	v_lshl_add_u64 v[4:5], s[26:27], 0, v[4:5]
	s_cmp_lt_i32 s15, 4
	s_mov_b64 s[16:17], 0x10300000
	v_lshl_add_u64 v[4:5], v[4:5], 0, v[186:187]
	s_cselect_b64 s[42:43], -1, 0
	s_ashr_i32 s65, s14, 7
	v_lshl_add_u64 v[190:191], v[4:5], 0, s[16:17]
	s_and_b32 s14, s15, 1
	s_add_i32 s67, 0, 0x1b480
	s_lshl_b32 s16, s65, 13
	s_lshl_b32 s17, s14, 3
	s_add_i32 s16, s67, s16
	s_cmp_eq_u32 s14, 0
	s_cselect_b64 s[44:45], -1, 0
	s_and_b32 s15, s15, 3
	v_and_b32_e32 v193, 15, v184
	v_bfe_u32 v9, v184, 4, 2
	s_movk_i32 s59, 0x90
	v_and_b32_e32 v11, 3, v184
	v_add_u32_e32 v206, s16, v202
	s_lshl_b32 s16, s15, 6
	v_and_b32_e32 v2, 48, v184
	v_mul_lo_u32 v12, v0, s59
	v_mov_b32_e32 v3, v187
	v_or_b32_e32 v205, s17, v9
	v_bitop3_b32 v4, s17, v193, v9 bitop3:0x36
	v_or3_b32 v192, v13, v11, s16
	v_lshl_or_b32 v208, v9, 3, s16
	v_lshl_add_u32 v223, v0, 2, s21
	v_and_b32_e32 v9, 15, v0
	v_lshl_add_u32 v11, v0, 8, 0
	v_lshl_add_u64 v[6:7], s[26:27], 0, v[2:3]
	v_add_u32_e32 v3, s23, v12
	v_mov_b32_e32 v1, v187
	s_mov_b64 s[18:19], 0x12300000
	s_lshl_b32 s68, s15, 11
	v_lshl_add_u64 v[188:189], v[6:7], 0, s[18:19]
	v_lshlrev_b32_e32 v195, 2, v184
	v_bitop3_b32 v5, v205, v193, 4 bitop3:0x36
	s_lshl_b32 s69, s65, 4
	s_movk_i32 s10, 0x100
	s_movk_i32 s8, 0x4000
	v_add_u32_e32 v203, s21, v195
	v_add_u32_e32 v228, 0, v195
	s_add_i32 s70, s69, 0
	s_mov_b32 s20, 0
	v_cmp_gt_i32_e64 s[6:7], 32, v184
	v_cmp_gt_i32_e64 s[8:9], s8, v184
	v_cmp_gt_i32_e64 s[10:11], s10, v184
	v_cmp_eq_u32_e64 s[12:13], 0, v10
	v_add_u32_e32 v204, s22, v195
	v_or_b32_e32 v207, 4, v205
	s_and_b64 s[46:47], s[44:45], vcc
	v_or_b32_e32 v209, 2, v208
	v_or_b32_e32 v210, 3, v208
	v_or_b32_e32 v211, 4, v208
	s_waitcnt vmcnt(0)
	v_mul_f32_e32 v217, 0x3fb8aa3b, v8
	v_lshlrev_b32_e32 v8, 3, v10
	v_bitop3_b32 v0, v8, v0, 15 bitop3:0x78
	v_lshlrev_b32_e32 v12, 4, v0
	v_and_b32_e32 v0, 63, v184
	v_lshlrev_b32_e32 v0, 4, v0

;     ...
;             const bf16_t* vp = Mvt + vrow + ((long)(j + 1) * 64 + dh * 32 + fr) * 256 + fq * 8;
	v_lshl_or_b32 v0, s14, 14, v0
	v_lshl_add_u64 v[0:1], s[26:27], 0, v[0:1]

; #define LAS __attribute__((address_space(3)))
;     ...
;   LAS float* oacc = (LAS float*)(shm + MO_OACC); LAS float* lsl = (LAS float*)(shm + MO_L); LAS float* kb = (LAS float*)(shm + MO_KBAR);
;   LAS int* cnt = (LAS int*)(shm + MO_CNT); LAS unsigned char* list = shm + MO_LIST; LAS unsigned char* Qs = shm + MO_Q; LAS unsigned char* Pb = shm + MO_P;
;   const int dtw = wid & 3, ttw = wid >> 2;
;   for (int u = blockIdx.x, it = 0; u < 1024; u += gridDim.x, ++it) {
;     int blk = 31 - (u >> 5), bh = u & 31;
;     if (gridDim.x == 256) {
;       const int x = blockIdx.x & 7, m = blockIdx.x >> 3, m2 = (m + 16) & 31;
;       bh = x + 8 * it; blk = it == 0 ? 31 - m : (it == 1 ? m : (it == 2 ? m2 : 31 - m2));
;     }
;     const long qbase = ((long)bh * SEQ + blk * 256) * 64;
;     for (int i = tid; i < 256 * 64; i += NTHREADS) oacc[i] = 0.f;
;     if (tid < 256) lsl[tid] = 0.f;
;     if (tid < 32) cnt[tid] = 0;
;     for (int i = tid; i < blk * 64; i += NTHREADS) kb[i] = kbarg[((long)bh * 32) * 64 + i];
;     const int qt = tid >> 1, qh = tid & 1;
	s_mov_b64 s[14:15], 0x14300000
	v_lshl_add_u64 v[196:197], v[0:1], 0, s[14:15]
	v_bitop3_b32 v0, v8, v9, 1 bitop3:0x36
	v_bitop3_b32 v1, v8, v9, 2 bitop3:0x36
	v_bitop3_b32 v6, v8, v9, 3 bitop3:0x36
	v_bitop3_b32 v7, v8, v9, 4 bitop3:0x36
	v_bitop3_b32 v13, v8, v9, 5 bitop3:0x36
	v_bitop3_b32 v14, v8, v9, 6 bitop3:0x36
	v_bitop3_b32 v8, v8, v9, 7 bitop3:0x36
	v_lshlrev_b32_e32 v9, 8, v193
	s_add_i32 s14, s67, s68
	v_lshl_or_b32 v9, s65, 12, v9
	v_lshlrev_b32_e32 v0, 4, v0
	v_add_u32_e32 v226, s14, v202
	s_lshl_b32 s14, s65, 6
	v_lshl_or_b32 v4, v4, 4, v9
	v_lshlrev_b32_e32 v1, 4, v1
	v_lshlrev_b32_e32 v6, 4, v6
	v_lshlrev_b32_e32 v7, 4, v7
	v_lshlrev_b32_e32 v13, 4, v13
	v_lshlrev_b32_e32 v14, 4, v14
	v_lshlrev_b32_e32 v8, 4, v8
	s_add_i32 s21, s21, s14
	v_lshl_or_b32 v5, v5, 4, v9
	v_add_u32_e32 v234, 0, v4
	v_mul_u32_u24_e32 v4, 0x90, v193
	v_add_u32_e32 v238, v11, v0
	v_mbcnt_lo_u32_b32 v0, -1, 0
	v_or_b32_e32 v212, 5, v208
	v_or_b32_e32 v213, 6, v208
	v_or_b32_e32 v214, 7, v208
	v_or_b32_e32 v215, 32, v208
	v_or_b32_e32 v216, 34, v208
	v_or_b32_e32 v218, 35, v208
	v_or_b32_e32 v219, 36, v208
	v_or_b32_e32 v220, 37, v208
	v_or_b32_e32 v221, 38, v208
	v_or_b32_e32 v222, 39, v208
	v_not_b32_e32 v224, v184
	v_add_u32_e32 v185, 0x200, v184
	v_add_u32_e32 v225, s23, v2
	v_add_u32_e32 v227, 0xfffffe00, v184
	v_add_u32_e32 v229, s67, v195
	v_add_u32_e32 v230, 0x1bc80, v228
	v_lshl_add_u32 v231, v10, 7, s67
	s_add_i32 s70, s70, 0x10380
	s_sub_i32 s71, 0, s69
	v_lshl_add_u32 v232, v193, 2, s21
	v_add_u32_e32 v233, 0, v5
	v_add3_u32 v235, v4, v2, s23
	s_movk_i32 s72, 0x3dff
	s_movk_i32 s73, 0x1ff
	s_mov_b64 s[48:49], 0x800
	v_add_u32_e32 v186, v3, v186
	v_mov_b32_e32 v236, 1
	s_add_i32 s75, 0, 0x10480
	s_add_i32 s76, 0, 0x10390
	v_add_u32_e32 v237, v11, v12
	v_add_u32_e32 v239, v11, v1
	v_add_u32_e32 v240, v11, v6
	v_add_u32_e32 v241, v11, v7
	v_add_u32_e32 v242, v11, v13
	v_add_u32_e32 v243, v11, v14
	v_add_u32_e32 v244, v11, v8
	v_mbcnt_hi_u32_b32 v245, -1, v0
	v_mov_b32_e32 v0, 0x3f803f80
	s_mov_b32 s77, s2
	s_mov_b32 s78, 0
	s_branch .LBB0_543

;     ...
;             const bf16_t* vp = Mvt + vrow + ((long)(j + 1) * 64 + dh * 32 + fr) * 256 + fq * 8;
; #pragma unroll
;             for (int a = 0; a < 2; ++a)
; #pragma unroll
;               for (int ks = 0; ks < 8; ++ks) vn[a][ks] = *(const bf16x8*)(vp + a * 16 * 256 + ks * 32);
.LBB0_592:
	s_add_i32 s56, s17, 1
	s_ashr_i32 s57, s56, 31
	s_lshl_b64 s[22:23], s[56:57], 15
	v_lshl_add_u64 v[2:3], v[200:201], 0, s[22:23]
	global_load_dwordx4 v[32:35], v[2:3], off
	global_load_dwordx4 v[40:43], v[2:3], off offset:1024
	global_load_dwordx4 v[44:47], v[2:3], off offset:2048
	global_load_dwordx4 v[48:51], v[2:3], off offset:3072
	v_add_co_u32_e32 v2, vcc, 0x1000, v2
	s_nop 1
	v_addc_co_u32_e32 v3, vcc, 0, v3, vcc
	global_load_dwordx4 v[52:55], v[2:3], off
	global_load_dwordx4 v[56:59], v[2:3], off offset:1024
	global_load_dwordx4 v[60:63], v[2:3], off offset:2048
	global_load_dwordx4 v[64:67], v[2:3], off offset:3072
	v_add_co_u32_e32 v2, vcc, 0x1000, v2
	s_nop 1
	v_addc_co_u32_e32 v3, vcc, 0, v3, vcc
	global_load_dwordx4 v[36:39], v[2:3], off
	global_load_dwordx4 v[28:31], v[2:3], off offset:1024
	global_load_dwordx4 v[24:27], v[2:3], off offset:2048
	global_load_dwordx4 v[20:23], v[2:3], off offset:3072
	v_add_co_u32_e32 v2, vcc, 0x1000, v2
	s_nop 1
	v_addc_co_u32_e32 v3, vcc, 0, v3, vcc
	global_load_dwordx4 v[16:19], v[2:3], off
	global_load_dwordx4 v[12:15], v[2:3], off offset:1024
	global_load_dwordx4 v[8:11], v[2:3], off offset:2048
	global_load_dwordx4 v[4:7], v[2:3], off offset:3072

; #define MO_BARRIER do { asm volatile("s_waitcnt lgkmcnt(0)" ::: "memory"); __builtin_amdgcn_s_barrier(); asm volatile("" ::: "memory"); } while (0)
;     ...
;           const int n = j < 0 ? 0 : (own ? 256 : cnt[j]), ntile = (n + 15) >> 4;
;     ...
;           if (first) { MO_BARRIER; first = false; }
;           psteps(j, std::false_type{});
	s_andn2_b64 vcc, exec, s[14:15]
	s_cbranch_vccz .LBB0_596
	s_cmp_lt_i32 s17, 0
	s_mov_b32 s14, 0
	s_cbranch_scc0 .LBB0_597

; #define LAS __attribute__((address_space(3)))
; DI u32x2 pk4(f32x4 v) { u32x2 r; r.x = pk2(v[0], v[1]); r.y = pk2(v[2], v[3]); return r; }
;     ...
;     {
;       LAS unsigned char* tb = shm + RO_TB + wid * RO_TBW;
; #pragma unroll
;       for (int nt = 0; nt < 8; ++nt) {
;         const f32x2 st = ((const LAS f32x2*)(shm + RO_STAT))[nt * 16 + fr];
; #pragma unroll
;         for (int e2 = 0; e2 < 2; ++e2) *(LAS u32x2*)(tb + (nt * 16 + fr) * 80 + (e2 * 16 + 4 * fq) * 2) = pk4((o[e2][nt] - st.x) * st.y);
;       }
;       asm volatile("s_waitcnt lgkmcnt(0)" ::: "memory");
.LBB0_728:
	s_or_b64 exec, exec, s[0:1]
	s_waitcnt lgkmcnt(0)
	s_barrier
	ds_read_b64 v[64:65], v123
	s_ashr_i32 s0, s46, 8
	s_ashr_i32 s1, s0, 31
	s_lshl_b64 s[0:1], s[0:1], 24
	s_add_u32 s0, s68, s0
	s_waitcnt lgkmcnt(0)
	v_sub_f32_e32 v45, v45, v64
	v_sub_f32_e32 v44, v44, v64
	v_sub_f32_e32 v47, v47, v64
	v_sub_f32_e32 v46, v46, v64
	v_sub_f32_e32 v37, v37, v64
	v_sub_f32_e32 v36, v36, v64
	v_sub_f32_e32 v39, v39, v64
	v_sub_f32_e32 v38, v38, v64
	v_pk_mul_f32 v[46:47], v[64:65], v[46:47] op_sel:[1,0]
	v_pk_mul_f32 v[44:45], v[64:65], v[44:45] op_sel:[1,0]
	v_pk_mul_f32 v[38:39], v[64:65], v[38:39] op_sel:[1,0]
	v_pk_mul_f32 v[36:37], v[64:65], v[36:37] op_sel:[1,0]
	v_cvt_pk_bf16_f32 v44, v44, v45
	v_cvt_pk_bf16_f32 v45, v46, v47
	v_cvt_pk_bf16_f32 v36, v36, v37
	v_cvt_pk_bf16_f32 v37, v38, v39
	ds_write2_b64 v137, v[44:45], v[36:37] offset1:4
	ds_read_b64 v[36:37], v124
	s_addc_u32 s1, s69, s1
	s_lshl_b32 s10, s46, 18
	s_and_b32 s10, s10, 0xfc0000
	s_add_u32 s0, s0, s10
	s_waitcnt lgkmcnt(0)
	v_sub_f32_e32 v5, v5, v36
	v_sub_f32_e32 v4, v4, v36
	v_sub_f32_e32 v7, v7, v36
	v_sub_f32_e32 v6, v6, v36
	v_pk_mul_f32 v[6:7], v[36:37], v[6:7] op_sel:[1,0]
	v_pk_mul_f32 v[4:5], v[36:37], v[4:5] op_sel:[1,0]
	s_addc_u32 s1, s1, 0
	v_cvt_pk_bf16_f32 v4, v4, v5
	v_cvt_pk_bf16_f32 v5, v6, v7
	v_sub_f32_e32 v7, v25, v36
	v_sub_f32_e32 v6, v24, v36
	v_sub_f32_e32 v25, v27, v36
	v_sub_f32_e32 v24, v26, v36
	v_pk_mul_f32 v[24:25], v[36:37], v[24:25] op_sel:[1,0]
	v_pk_mul_f32 v[6:7], v[36:37], v[6:7] op_sel:[1,0]
	s_lshl_b32 s10, s52, 9
	v_cvt_pk_bf16_f32 v6, v6, v7
	v_cvt_pk_bf16_f32 v7, v24, v25
	ds_write2_b64 v137, v[4:5], v[6:7] offset0:160 offset1:164
	ds_read_b64 v[4:5], v125
	s_add_u32 s0, s0, s10
	s_addc_u32 s1, s1, 0
	s_add_u32 s0, s0, s44
	s_addc_u32 s1, s1, s45
	s_waitcnt lgkmcnt(0)
	v_sub_f32_e32 v7, v9, v4
	v_sub_f32_e32 v6, v8, v4
	v_sub_f32_e32 v9, v11, v4
	v_sub_f32_e32 v8, v10, v4
	v_pk_mul_f32 v[8:9], v[4:5], v[8:9] op_sel:[1,0]
	v_pk_mul_f32 v[6:7], v[4:5], v[6:7] op_sel:[1,0]
	v_sub_f32_e32 v11, v23, v4
	v_cvt_pk_bf16_f32 v6, v6, v7
	v_cvt_pk_bf16_f32 v7, v8, v9
	v_sub_f32_e32 v9, v21, v4
	v_sub_f32_e32 v8, v20, v4
	v_sub_f32_e32 v10, v22, v4
	v_pk_mul_f32 v[10:11], v[4:5], v[10:11] op_sel:[1,0]
	v_pk_mul_f32 v[4:5], v[4:5], v[8:9] op_sel:[1,0]
	v_add_u32_e32 v8, 0x800, v137
	v_cvt_pk_bf16_f32 v4, v4, v5
	v_cvt_pk_bf16_f32 v5, v10, v11
	ds_write2_b64 v8, v[6:7], v[4:5] offset0:64 offset1:68
	ds_read_b64 v[4:5], v126
	v_mov_b32_e32 v101, v91
	v_mov_b32_e32 v103, v91
	v_lshl_add_u64 v[20:21], s[0:1], 0, v[102:103]
	v_mov_b32_e32 v105, v91
	s_waitcnt lgkmcnt(0)
	v_sub_f32_e32 v1, v1, v4
	v_sub_f32_e32 v0, v0, v4
	v_sub_f32_e32 v3, v3, v4
	v_sub_f32_e32 v2, v2, v4
	v_pk_mul_f32 v[2:3], v[4:5], v[2:3] op_sel:[1,0]
	v_pk_mul_f32 v[0:1], v[4:5], v[0:1] op_sel:[1,0]
	v_sub_f32_e32 v7, v19, v4
	v_cvt_pk_bf16_f32 v0, v0, v1
	v_cvt_pk_bf16_f32 v1, v2, v3
	v_sub_f32_e32 v3, v17, v4
	v_sub_f32_e32 v2, v16, v4
	v_sub_f32_e32 v6, v18, v4
	v_pk_mul_f32 v[6:7], v[4:5], v[6:7] op_sel:[1,0]
	v_pk_mul_f32 v[2:3], v[4:5], v[2:3] op_sel:[1,0]
	v_mov_b32_e32 v107, v91
	v_cvt_pk_bf16_f32 v2, v2, v3
	v_cvt_pk_bf16_f32 v3, v6, v7
	ds_write2_b64 v8, v[0:1], v[2:3] offset0:224 offset1:228
	ds_read_b64 v[0:1], v127
	v_add_u32_e32 v8, 0x1800, v137
	v_mov_b32_e32 v109, v91
	v_mov_b32_e32 v111, v91
	v_mov_b32_e32 v113, v91
	s_waitcnt lgkmcnt(0)
	v_sub_f32_e32 v3, v41, v0
	v_sub_f32_e32 v2, v40, v0
	v_sub_f32_e32 v5, v43, v0
	v_sub_f32_e32 v4, v42, v0
	v_pk_mul_f32 v[4:5], v[0:1], v[4:5] op_sel:[1,0]
	v_pk_mul_f32 v[2:3], v[0:1], v[2:3] op_sel:[1,0]
	v_sub_f32_e32 v7, v31, v0
	v_cvt_pk_bf16_f32 v2, v2, v3
	v_cvt_pk_bf16_f32 v3, v4, v5
	v_sub_f32_e32 v5, v29, v0
	v_sub_f32_e32 v4, v28, v0
	v_sub_f32_e32 v6, v30, v0
	v_pk_mul_f32 v[6:7], v[0:1], v[6:7] op_sel:[1,0]
	v_pk_mul_f32 v[0:1], v[0:1], v[4:5] op_sel:[1,0]
	v_add_u32_e32 v4, 0x1000, v137
	v_cvt_pk_bf16_f32 v0, v0, v1
	v_cvt_pk_bf16_f32 v1, v6, v7
	ds_write2_b64 v4, v[2:3], v[0:1] offset0:128 offset1:132
	ds_read_b64 v[0:1], v128
	v_mov_b32_e32 v115, v91
	v_mov_b32_e32 v117, v91
	v_mov_b32_e32 v119, v91
	s_add_i32 s46, s46, s28
	s_waitcnt lgkmcnt(0)
	v_sub_f32_e32 v3, v13, v0
	v_sub_f32_e32 v2, v12, v0
	v_sub_f32_e32 v5, v15, v0
	v_sub_f32_e32 v4, v14, v0
	v_pk_mul_f32 v[4:5], v[0:1], v[4:5] op_sel:[1,0]
	v_pk_mul_f32 v[2:3], v[0:1], v[2:3] op_sel:[1,0]
	v_sub_f32_e32 v7, v35, v0
	v_cvt_pk_bf16_f32 v2, v2, v3
	v_cvt_pk_bf16_f32 v3, v4, v5
	v_sub_f32_e32 v5, v33, v0
	v_sub_f32_e32 v4, v32, v0
	v_sub_f32_e32 v6, v34, v0
	v_pk_mul_f32 v[6:7], v[0:1], v[6:7] op_sel:[1,0]
	v_pk_mul_f32 v[0:1], v[0:1], v[4:5] op_sel:[1,0]
	s_cmpk_lt_i32 s46, 0x400
	v_cvt_pk_bf16_f32 v0, v0, v1
	v_cvt_pk_bf16_f32 v1, v6, v7
	ds_write2_b64 v8, v[2:3], v[0:1] offset0:32 offset1:36
	ds_read_b64 v[0:1], v129
	s_waitcnt lgkmcnt(0)
	v_sub_f32_e32 v3, v53, v0
	v_sub_f32_e32 v2, v52, v0
	v_sub_f32_e32 v5, v55, v0
	v_sub_f32_e32 v4, v54, v0
	v_pk_mul_f32 v[4:5], v[0:1], v[4:5] op_sel:[1,0]
	v_pk_mul_f32 v[2:3], v[0:1], v[2:3] op_sel:[1,0]
	v_sub_f32_e32 v7, v51, v0
	v_cvt_pk_bf16_f32 v2, v2, v3
	v_cvt_pk_bf16_f32 v3, v4, v5
	v_sub_f32_e32 v5, v49, v0
	v_sub_f32_e32 v4, v48, v0
	v_sub_f32_e32 v6, v50, v0
	v_pk_mul_f32 v[6:7], v[0:1], v[6:7] op_sel:[1,0]
	v_pk_mul_f32 v[0:1], v[0:1], v[4:5] op_sel:[1,0]
	s_nop 0
	v_cvt_pk_bf16_f32 v0, v0, v1
	v_cvt_pk_bf16_f32 v1, v6, v7
	ds_write2_b64 v8, v[2:3], v[0:1] offset0:192 offset1:196
	ds_read_b64 v[0:1], v130
	s_waitcnt lgkmcnt(0)
; #define LAS __attribute__((address_space(3)))
; DI unsigned pk2(float lo, float hi) { f32x2 v = {lo, hi}; bf16v2 b = __builtin_convertvector(v, bf16v2); return __builtin_bit_cast(unsigned, b); }
; DI f32x4 unpk4(u32x2 u) { f32x4 r; r[0] = __uint_as_float(u.x << 16); r[1] = __uint_as_float(u.x & 0xffff0000u); r[2] = __uint_as_float(u.y << 16); r[3] = __uint_as_float(u.y & 0xffff0000u); return r; }
;     ...
;       bf16_t* gbase = G + ((long)b * SEQ + c * 128) * 1024 + h * 256 + 32 * wid;
;       bf16_t* obase = dry ? (bf16_t*)((unsigned char*)p.out + 64 * MiB) + (gbase - G) : gbase;
;       u32x4 gv[8];
; #pragma unroll
;       for (int r = 0; r < 8; ++r) { const int idx = r * 64 + lane; gv[r] = *(const u32x4*)(gbase + (long)(idx >> 2) * 1024 + (idx & 3) * 8); }
; #pragma unroll
;       for (int r = 0; r < 8; ++r) {
;         const int idx = r * 64 + lane, nn = idx >> 2, ch = idx & 3;
;         const u32x4 ov = *(const LAS u32x4*)(tb + nn * 80 + ch * 16);
;         u32x4 w4;
;         { const f32x4 a = unpk4((u32x2){ov.x, ov.y}) * unpk4((u32x2){gv[r].x, gv[r].y}), c2 = unpk4((u32x2){ov.z, ov.w}) * unpk4((u32x2){gv[r].z, gv[r].w});
;           w4.x = pk2(a[0], a[1]); w4.y = pk2(a[2], a[3]); w4.z = pk2(c2[0], c2[1]); w4.w = pk2(c2[2], c2[3]); }
;         *(u32x4*)(obase + (long)nn * 1024 + ch * 8) = w4;
	v_sub_f32_e32 v3, v61, v0
	v_sub_f32_e32 v2, v60, v0
	v_sub_f32_e32 v5, v63, v0
	v_sub_f32_e32 v4, v62, v0
	v_pk_mul_f32 v[4:5], v[0:1], v[4:5] op_sel:[1,0]
	v_pk_mul_f32 v[2:3], v[0:1], v[2:3] op_sel:[1,0]
	v_sub_f32_e32 v7, v59, v0
	v_cvt_pk_bf16_f32 v2, v2, v3
	v_cvt_pk_bf16_f32 v3, v4, v5
	v_sub_f32_e32 v5, v57, v0
	v_sub_f32_e32 v4, v56, v0
	v_sub_f32_e32 v6, v58, v0
	v_pk_mul_f32 v[6:7], v[0:1], v[6:7] op_sel:[1,0]
	v_pk_mul_f32 v[0:1], v[0:1], v[4:5] op_sel:[1,0]
	v_add_u32_e32 v4, 0x2000, v137
	v_cvt_pk_bf16_f32 v0, v0, v1
	v_cvt_pk_bf16_f32 v1, v6, v7
	ds_write2_b64 v4, v[2:3], v[0:1] offset0:96 offset1:100
	v_lshl_add_u64 v[0:1], s[0:1], 0, v[90:91]
	s_waitcnt lgkmcnt(0)
	v_lshl_add_u64 v[0:1], v[0:1], 0, v[100:101]
	global_load_dwordx4 v[22:25], v[0:1], off
	v_add_co_u32_e32 v2, vcc, s31, v0
	s_nop 1
	v_addc_co_u32_e32 v3, vcc, 0, v1, vcc
	global_load_dwordx4 v[26:29], v[2:3], off
	v_add_co_u32_e32 v2, vcc, s38, v0
	s_nop 1
	v_addc_co_u32_e32 v3, vcc, 0, v1, vcc
	v_add_co_u32_e32 v4, vcc, s19, v0
	s_nop 1
	v_addc_co_u32_e32 v5, vcc, 0, v1, vcc
	global_load_dwordx4 v[30:33], v[2:3], off
	global_load_dwordx4 v[16:19], v[4:5], off
	v_add_co_u32_e32 v2, vcc, s48, v0
	s_nop 1
	v_addc_co_u32_e32 v3, vcc, 0, v1, vcc
	v_add_co_u32_e32 v4, vcc, s49, v0
	s_nop 1
	v_addc_co_u32_e32 v5, vcc, 0, v1, vcc
	global_load_dwordx4 v[12:15], v[2:3], off
	global_load_dwordx4 v[8:11], v[4:5], off
	v_add_co_u32_e32 v2, vcc, s50, v0
	ds_read_b128 v[34:37], v138
	s_nop 0
	v_addc_co_u32_e32 v3, vcc, 0, v1, vcc
	v_add_co_u32_e32 v0, vcc, s51, v0
	s_waitcnt lgkmcnt(0)
	v_lshlrev_b32_e32 v42, 16, v34
	v_addc_co_u32_e32 v1, vcc, 0, v1, vcc
	global_load_dwordx4 v[4:7], v[2:3], off
	s_nop 0
	global_load_dwordx4 v[0:3], v[0:1], off
	s_waitcnt vmcnt(7)
	v_lshlrev_b32_e32 v44, 16, v22
	v_and_b32_e32 v45, 0xffff0000, v22
	v_lshlrev_b32_e32 v22, 16, v23
	v_and_b32_e32 v23, 0xffff0000, v23
	ds_read_b128 v[38:41], v139
	v_and_b32_e32 v43, 0xffff0000, v34
	v_lshlrev_b32_e32 v34, 16, v35
	v_and_b32_e32 v35, 0xffff0000, v35
	v_pk_mul_f32 v[34:35], v[22:23], v[34:35]
	v_pk_mul_f32 v[22:23], v[44:45], v[42:43]
	v_lshlrev_b32_e32 v42, 16, v36
	v_and_b32_e32 v43, 0xffff0000, v36
	v_lshlrev_b32_e32 v36, 16, v37
	v_and_b32_e32 v37, 0xffff0000, v37
	v_lshlrev_b32_e32 v44, 16, v24
	v_and_b32_e32 v45, 0xffff0000, v24
	v_lshlrev_b32_e32 v24, 16, v25
	v_and_b32_e32 v25, 0xffff0000, v25
	v_pk_mul_f32 v[36:37], v[24:25], v[36:37]
	v_pk_mul_f32 v[24:25], v[44:45], v[42:43]
	v_cvt_pk_bf16_f32 v22, v22, v23
	v_cvt_pk_bf16_f32 v23, v34, v35
	v_cvt_pk_bf16_f32 v24, v24, v25
	v_cvt_pk_bf16_f32 v25, v36, v37
	v_lshl_add_u64 v[34:35], v[20:21], 0, v[104:105]
	global_store_dwordx4 v[34:35], v[22:25], off
	s_waitcnt vmcnt(7)
	v_lshlrev_b32_e32 v34, 16, v26
	v_and_b32_e32 v35, 0xffff0000, v26
	s_waitcnt lgkmcnt(0)
	v_lshlrev_b32_e32 v22, 16, v38
	v_and_b32_e32 v23, 0xffff0000, v38
	v_lshlrev_b32_e32 v24, 16, v39
	v_and_b32_e32 v25, 0xffff0000, v39
	v_lshlrev_b32_e32 v26, 16, v27
	v_and_b32_e32 v27, 0xffff0000, v27
	v_pk_mul_f32 v[24:25], v[26:27], v[24:25]
	v_pk_mul_f32 v[22:23], v[34:35], v[22:23]
	v_lshlrev_b32_e32 v26, 16, v40
	v_and_b32_e32 v27, 0xffff0000, v40
	v_lshlrev_b32_e32 v34, 16, v41
	v_and_b32_e32 v35, 0xffff0000, v41
	v_lshlrev_b32_e32 v36, 16, v28
	v_and_b32_e32 v37, 0xffff0000, v28
	v_lshlrev_b32_e32 v28, 16, v29
	v_and_b32_e32 v29, 0xffff0000, v29
	v_pk_mul_f32 v[28:29], v[28:29], v[34:35]
	v_pk_mul_f32 v[26:27], v[36:37], v[26:27]
	v_cvt_pk_bf16_f32 v22, v22, v23
	v_cvt_pk_bf16_f32 v23, v24, v25
	v_cvt_pk_bf16_f32 v24, v26, v27
	v_cvt_pk_bf16_f32 v25, v28, v29
	ds_read_b128 v[26:29], v139 offset:1280
	v_lshl_add_u64 v[34:35], v[20:21], 0, v[106:107]
	global_store_dwordx4 v[34:35], v[22:25], off
	ds_read_b128 v[22:25], v139 offset:2560
	s_waitcnt lgkmcnt(1)
	v_lshlrev_b32_e32 v34, 16, v26
	v_and_b32_e32 v35, 0xffff0000, v26
	v_lshlrev_b32_e32 v26, 16, v27
	v_and_b32_e32 v27, 0xffff0000, v27
	s_waitcnt vmcnt(7)
	v_lshlrev_b32_e32 v36, 16, v30
	v_and_b32_e32 v37, 0xffff0000, v30
	v_lshlrev_b32_e32 v30, 16, v31
	v_and_b32_e32 v31, 0xffff0000, v31
	v_pk_mul_f32 v[30:31], v[30:31], v[26:27]
	v_pk_mul_f32 v[26:27], v[36:37], v[34:35]
	v_lshlrev_b32_e32 v34, 16, v28
	v_and_b32_e32 v35, 0xffff0000, v28
	v_lshlrev_b32_e32 v28, 16, v29
	v_and_b32_e32 v29, 0xffff0000, v29
	v_lshlrev_b32_e32 v36, 16, v32
	v_and_b32_e32 v37, 0xffff0000, v32
	v_lshlrev_b32_e32 v32, 16, v33
	v_and_b32_e32 v33, 0xffff0000, v33
	v_pk_mul_f32 v[32:33], v[32:33], v[28:29]
	v_pk_mul_f32 v[28:29], v[36:37], v[34:35]
	v_cvt_pk_bf16_f32 v26, v26, v27
	v_cvt_pk_bf16_f32 v27, v30, v31
	v_cvt_pk_bf16_f32 v28, v28, v29
	v_cvt_pk_bf16_f32 v29, v32, v33
	v_lshl_add_u64 v[30:31], v[20:21], 0, v[108:109]
	global_store_dwordx4 v[30:31], v[26:29], off
	s_waitcnt lgkmcnt(0)
	s_nop 0
	v_lshlrev_b32_e32 v26, 16, v22
	v_and_b32_e32 v27, 0xffff0000, v22
	v_lshlrev_b32_e32 v22, 16, v23
	v_and_b32_e32 v23, 0xffff0000, v23
	s_waitcnt vmcnt(7)
; #define LAS __attribute__((address_space(3)))
; DI unsigned pk2(float lo, float hi) { f32x2 v = {lo, hi}; bf16v2 b = __builtin_convertvector(v, bf16v2); return __builtin_bit_cast(unsigned, b); }
; DI f32x4 unpk4(u32x2 u) { f32x4 r; r[0] = __uint_as_float(u.x << 16); r[1] = __uint_as_float(u.x & 0xffff0000u); r[2] = __uint_as_float(u.y << 16); r[3] = __uint_as_float(u.y & 0xffff0000u); return r; }
;     ...
; #pragma unroll
;       for (int r = 0; r < 8; ++r) {
;         const int idx = r * 64 + lane, nn = idx >> 2, ch = idx & 3;
;         const u32x4 ov = *(const LAS u32x4*)(tb + nn * 80 + ch * 16);
;         u32x4 w4;
;         { const f32x4 a = unpk4((u32x2){ov.x, ov.y}) * unpk4((u32x2){gv[r].x, gv[r].y}), c2 = unpk4((u32x2){ov.z, ov.w}) * unpk4((u32x2){gv[r].z, gv[r].w});
;           w4.x = pk2(a[0], a[1]); w4.y = pk2(a[2], a[3]); w4.z = pk2(c2[0], c2[1]); w4.w = pk2(c2[2], c2[3]); }
;         *(u32x4*)(obase + (long)nn * 1024 + ch * 8) = w4;
	v_lshlrev_b32_e32 v28, 16, v16
	v_and_b32_e32 v29, 0xffff0000, v16
	v_lshlrev_b32_e32 v16, 16, v17
	v_and_b32_e32 v17, 0xffff0000, v17
	v_pk_mul_f32 v[22:23], v[16:17], v[22:23]
	v_pk_mul_f32 v[16:17], v[28:29], v[26:27]
	v_lshlrev_b32_e32 v26, 16, v24
	v_and_b32_e32 v27, 0xffff0000, v24
	v_lshlrev_b32_e32 v24, 16, v25
	v_and_b32_e32 v25, 0xffff0000, v25
	v_lshlrev_b32_e32 v28, 16, v18
	v_and_b32_e32 v29, 0xffff0000, v18
	v_lshlrev_b32_e32 v18, 16, v19
	v_and_b32_e32 v19, 0xffff0000, v19
	v_pk_mul_f32 v[24:25], v[18:19], v[24:25]
	v_pk_mul_f32 v[18:19], v[28:29], v[26:27]
	v_cvt_pk_bf16_f32 v16, v16, v17
	v_cvt_pk_bf16_f32 v17, v22, v23
	v_cvt_pk_bf16_f32 v18, v18, v19
	v_cvt_pk_bf16_f32 v19, v24, v25
	ds_read_b128 v[22:25], v139 offset:3840
	v_lshl_add_u64 v[26:27], v[20:21], 0, v[110:111]
	global_store_dwordx4 v[26:27], v[16:19], off
	ds_read_b128 v[16:19], v139 offset:5120
	s_waitcnt vmcnt(7)
	v_lshlrev_b32_e32 v28, 16, v12
	s_waitcnt lgkmcnt(1)
	v_lshlrev_b32_e32 v26, 16, v22
	v_and_b32_e32 v27, 0xffff0000, v22
	v_lshlrev_b32_e32 v22, 16, v23
	v_and_b32_e32 v23, 0xffff0000, v23
	v_and_b32_e32 v29, 0xffff0000, v12
	v_lshlrev_b32_e32 v12, 16, v13
	v_and_b32_e32 v13, 0xffff0000, v13
	v_pk_mul_f32 v[22:23], v[12:13], v[22:23]
	v_pk_mul_f32 v[12:13], v[28:29], v[26:27]
	v_lshlrev_b32_e32 v26, 16, v24
	v_and_b32_e32 v27, 0xffff0000, v24
	v_lshlrev_b32_e32 v24, 16, v25
	v_and_b32_e32 v25, 0xffff0000, v25
	v_lshlrev_b32_e32 v28, 16, v14
	v_and_b32_e32 v29, 0xffff0000, v14
	v_lshlrev_b32_e32 v14, 16, v15
	v_and_b32_e32 v15, 0xffff0000, v15
	v_pk_mul_f32 v[24:25], v[14:15], v[24:25]
	v_pk_mul_f32 v[14:15], v[28:29], v[26:27]
	v_cvt_pk_bf16_f32 v12, v12, v13
	v_cvt_pk_bf16_f32 v13, v22, v23
	v_cvt_pk_bf16_f32 v14, v14, v15
	v_cvt_pk_bf16_f32 v15, v24, v25
	v_lshl_add_u64 v[22:23], v[20:21], 0, v[112:113]
	global_store_dwordx4 v[22:23], v[12:15], off
	s_waitcnt lgkmcnt(0)
	s_nop 0
	v_lshlrev_b32_e32 v12, 16, v16
	v_and_b32_e32 v13, 0xffff0000, v16
	v_lshlrev_b32_e32 v14, 16, v17
	v_and_b32_e32 v15, 0xffff0000, v17
	s_waitcnt vmcnt(7)
	v_lshlrev_b32_e32 v16, 16, v8
	v_and_b32_e32 v17, 0xffff0000, v8
	v_lshlrev_b32_e32 v8, 16, v9
	v_and_b32_e32 v9, 0xffff0000, v9
	v_pk_mul_f32 v[14:15], v[8:9], v[14:15]
	v_pk_mul_f32 v[8:9], v[16:17], v[12:13]
	v_lshlrev_b32_e32 v12, 16, v18
	v_and_b32_e32 v13, 0xffff0000, v18
	v_lshlrev_b32_e32 v16, 16, v19
	v_and_b32_e32 v17, 0xffff0000, v19
	v_lshlrev_b32_e32 v18, 16, v10
	v_and_b32_e32 v19, 0xffff0000, v10
	v_lshlrev_b32_e32 v10, 16, v11
	v_and_b32_e32 v11, 0xffff0000, v11
	v_pk_mul_f32 v[16:17], v[10:11], v[16:17]
	v_pk_mul_f32 v[10:11], v[18:19], v[12:13]
	v_cvt_pk_bf16_f32 v8, v8, v9
	v_cvt_pk_bf16_f32 v9, v14, v15
	ds_read_b128 v[12:15], v139 offset:6400
	v_cvt_pk_bf16_f32 v10, v10, v11
	v_cvt_pk_bf16_f32 v11, v16, v17
	v_lshl_add_u64 v[16:17], v[20:21], 0, v[114:115]
	global_store_dwordx4 v[16:17], v[8:11], off
	ds_read_b128 v[8:11], v139 offset:7680
	s_waitcnt lgkmcnt(1)
	v_lshlrev_b32_e32 v16, 16, v12
	v_and_b32_e32 v17, 0xffff0000, v12
	v_lshlrev_b32_e32 v12, 16, v13
	v_and_b32_e32 v13, 0xffff0000, v13
	s_waitcnt vmcnt(7)
	v_lshlrev_b32_e32 v18, 16, v4
	v_and_b32_e32 v19, 0xffff0000, v4
	v_lshlrev_b32_e32 v4, 16, v5
	v_and_b32_e32 v5, 0xffff0000, v5
	v_pk_mul_f32 v[12:13], v[4:5], v[12:13]
	v_pk_mul_f32 v[4:5], v[18:19], v[16:17]
	v_lshlrev_b32_e32 v16, 16, v14
	v_and_b32_e32 v17, 0xffff0000, v14
	v_lshlrev_b32_e32 v14, 16, v15
	v_and_b32_e32 v15, 0xffff0000, v15
	v_lshlrev_b32_e32 v18, 16, v6
	v_and_b32_e32 v19, 0xffff0000, v6
	v_lshlrev_b32_e32 v6, 16, v7
	v_and_b32_e32 v7, 0xffff0000, v7
	v_pk_mul_f32 v[14:15], v[6:7], v[14:15]
	v_pk_mul_f32 v[6:7], v[18:19], v[16:17]
	v_cvt_pk_bf16_f32 v4, v4, v5
	v_cvt_pk_bf16_f32 v5, v12, v13
	v_cvt_pk_bf16_f32 v6, v6, v7
	v_cvt_pk_bf16_f32 v7, v14, v15
	v_lshl_add_u64 v[12:13], v[20:21], 0, v[116:117]
	global_store_dwordx4 v[12:13], v[4:7], off
	s_waitcnt lgkmcnt(0)
	s_nop 0
	v_lshlrev_b32_e32 v4, 16, v8
	v_and_b32_e32 v5, 0xffff0000, v8
	v_lshlrev_b32_e32 v6, 16, v9
	v_and_b32_e32 v7, 0xffff0000, v9
	s_waitcnt vmcnt(7)
	v_lshlrev_b32_e32 v8, 16, v0
	v_and_b32_e32 v9, 0xffff0000, v0
	v_lshlrev_b32_e32 v0, 16, v1
	v_and_b32_e32 v1, 0xffff0000, v1
	v_pk_mul_f32 v[6:7], v[0:1], v[6:7]
	v_pk_mul_f32 v[0:1], v[8:9], v[4:5]
	v_lshlrev_b32_e32 v4, 16, v10
	v_and_b32_e32 v5, 0xffff0000, v10
	v_lshlrev_b32_e32 v8, 16, v11
	v_and_b32_e32 v9, 0xffff0000, v11
	v_lshlrev_b32_e32 v10, 16, v2
	v_and_b32_e32 v11, 0xffff0000, v2
	v_lshlrev_b32_e32 v2, 16, v3
	v_and_b32_e32 v3, 0xffff0000, v3
	v_pk_mul_f32 v[8:9], v[2:3], v[8:9]
	v_pk_mul_f32 v[2:3], v[10:11], v[4:5]
	v_cvt_pk_bf16_f32 v0, v0, v1
	v_cvt_pk_bf16_f32 v1, v6, v7
	v_cvt_pk_bf16_f32 v2, v2, v3
	v_cvt_pk_bf16_f32 v3, v8, v9
	v_lshl_add_u64 v[4:5], v[20:21], 0, v[118:119]
	global_store_dwordx4 v[4:5], v[0:3], off
	s_barrier
	s_cbranch_scc0 .LBB0_755
